# static s_setprio 1 for waves 4-7 across the attention phases A1-A3 (reset to 0 before the following grid barrier)
# baseline (speedup 1.0000x reference)
; #define LAS __attribute__((address_space(3)))
; template <int PARTS> DI void idx_unit(const bf16_t* PROJ, unsigned long long* MASK64, float* scr, LAS unsigned char* lds, int b, int qb, int tid, int wave, int lane) {
;     const int q0 = qb * 32;
;     const size_t rowbase = (size_t)b * SEQ;
;     float zf_ = 0.f; asm volatile("" : "+v"(zf_));
;     if (q0 < 256) {
; #pragma unroll 1
;         for (int rr = 0; rr < 4; ++rr) { const int t = q0 + wave * 4 + rr;
;             if (lane < 32) { const int lo = 64 * lane; const unsigned long long w = (t >= lo + 63) ? ~0ull : (t < lo ? 0ull : ((1ull << (t - lo + 1)) - 1ull)); MASK64[(rowbase + t) * 32 + lane] = w; } }
;         return;
;     }
;     LAS float* wl = (LAS float*)lds;
;     if (tid < 128) { const int q = tid >> 2, hh = tid & 3; wl[tid] = __uint_as_float((unsigned)PROJ[(rowbase + q0 + q) * NINP + C_WI + hh] << 16); }
;     const int r = lane & 31, h = lane >> 5;
;     constexpr int QP = 528;
;     LAS unsigned char* ql = lds + 512;
; #pragma unroll
;     for (int p = 0; p < 2; ++p) { const int idx = tid + 512 * p, row = idx >> 5, ch = idx & 31;
;         *(LAS u32x4*)(ql + row * QP + ch * 16) = *(const u32x4*)(PROJ + (rowbase + q0 + row) * NINP + C_QI + ch * 8); }
;     __syncthreads();
;     const int nkb = (PARTS & 1) ? q0 / 32 + 1 : 0;
;     bf16x8 kfn[4];
; #pragma unroll
;     for (int ks = 0; ks < 4; ++ks) kfn[ks] = *(const bf16x8*)(PROJ + (rowbase + (wave < nkb ? wave : 0) * 32 + r) * NINP + C_KI + ks * 16 + h * 8);
; __global__ void __launch_bounds__(NTHR, 2) hybrid_fwd(Args a_unused) {
;     ...
;         { PH_BEGIN;
;             float* scr = (float*)(ws + WS_XN) + (size_t)bx * 32 * SEQ;
; #pragma unroll 1
;             for (int k = 0; vcu + (k >> 1) * G < NB * 32; ++k) { const int u = k, pr = vcu + (k >> 1) * G, b = pr >> 5, j = pr & 31;
;                 idx_unit<3>(PROJ_, (unsigned long long*)(ws + WS_MASK), scr, lds, b, (u & 1) ? j : 63 - j, tid, wave, lane);
.LBB0_431:
	s_or_b64 exec, exec, s[0:1]
	s_mov_b64 s[0:1], s[66:67]
	s_mov_b32 s2, s73
	s_waitcnt lgkmcnt(0)
	s_barrier
	s_cmp_ge_u32 s73, 4
	s_cbranch_scc0 .Lmy_prio_skip
	s_setprio 1
.Lmy_prio_skip:
	v_mbcnt_lo_u32_b32 v96, -1, 0
	v_mbcnt_hi_u32_b32 v96, -1, v96
	s_nop 0
	v_writelane_b32 v254, s2, 1
	v_readlane_b32 s2, v253, 20
	v_readlane_b32 s3, v253, 21
	s_and_b64 vcc, exec, s[2:3]
	s_cbranch_vccz .LBB0_493
	s_load_dwordx2 s[0:1], s[0:1], 0xc8
	v_readlane_b32 s4, v254, 1
	s_movk_i32 s2, 0x80
	v_and_b32_e32 v202, 31, v96
	v_lshl_add_u32 v1, s4, 6, v96
	v_cmp_gt_i32_e64 s[2:3], s2, v1
	v_ashrrev_i32_e32 v200, 2, v1
	v_lshl_add_u32 v203, v1, 2, 0
	v_writelane_b32 v254, s2, 2
	v_ashrrev_i32_e32 v204, 5, v1
	v_add_u32_e32 v1, 0x200, v1
	v_writelane_b32 v254, s3, 3
	v_readlane_b32 s2, v253, 6
	v_readlane_b32 s3, v253, 7
	s_waitcnt lgkmcnt(0)
	s_add_u32 s2, s0, s2
	s_addc_u32 s3, s1, s3
	s_add_u32 s52, s2, 0x5200000
	s_addc_u32 s53, s3, 0
	s_add_u32 s2, s0, 0x9200000
	s_addc_u32 s3, s1, 0
	s_add_u32 s6, s0, 0x1d600000
	s_movk_i32 s0, 0x210
	v_ashrrev_i32_e32 v206, 5, v1
	s_addc_u32 s7, s1, 0
	v_mul_lo_u32 v7, v204, s0
	v_mul_lo_u32 v1, v206, s0
	s_lshl_b32 s0, s4, 5
	s_ashr_i32 s1, s0, 31
	v_mov_b32_e32 v209, s1
	s_lshl_b32 s1, s4, 2
	v_cmp_gt_i32_e64 s[4:5], 32, v96
	v_lshlrev_b32_e32 v2, 4, v202
	v_mov_b32_e32 v3, v98
	v_writelane_b32 v254, s4, 4
	v_ashrrev_i32_e32 v8, 5, v96
	v_lshl_add_u64 v[214:215], s[2:3], 0, v[2:3]
	v_writelane_b32 v254, s5, 5
	v_cmp_eq_u32_e64 s[4:5], 30, v96
	v_add_u32_e32 v6, 0, v2
	v_lshl_add_u32 v2, v8, 13, s0
	v_writelane_b32 v254, s4, 6
	v_lshlrev_b32_e32 v237, 6, v96
	v_or_b32_e32 v2, v2, v202
	v_writelane_b32 v254, s5, 7
	v_cmp_eq_u32_e64 s[4:5], 29, v96
	v_or_b32_e32 v208, s0, v202
	v_add_u32_e32 v238, 0xd800, v2
	v_writelane_b32 v254, s4, 8
	v_sub_u32_e32 v2, s1, v237
	v_readlane_b32 s0, v253, 19
	v_writelane_b32 v254, s5, 9
	v_cmp_eq_u32_e64 s[4:5], 28, v96
	v_cmp_eq_u32_e64 s[54:55], 7, v96
	v_cmp_eq_u32_e64 s[56:57], 6, v96
	v_writelane_b32 v254, s4, 10
	v_cmp_eq_u32_e64 s[66:67], 5, v96
	v_cmp_eq_u32_e64 s[68:69], 4, v96
	v_writelane_b32 v254, s5, 11
	v_cmp_eq_u32_e64 s[4:5], 27, v96
	v_lshlrev_b32_e32 v4, 3, v8
	v_cmp_eq_u32_e64 s[70:71], 3, v96
	v_writelane_b32 v254, s4, 12
	v_and_b32_e32 v0, 3, v96
	v_ashrrev_i32_e32 v5, 31, v4
	v_writelane_b32 v254, s5, 13
	v_cmp_eq_u32_e64 s[4:5], 26, v96
	v_lshl_add_u32 v9, v202, 9, v6
	v_lshlrev_b32_e32 v10, 4, v8
	v_writelane_b32 v254, s4, 14
	v_ashrrev_i32_e32 v97, 31, v96
	v_ashrrev_i32_e32 v201, 31, v200
	v_writelane_b32 v254, s5, 15
	v_cmp_eq_u32_e64 s[4:5], 25, v96
	v_ashrrev_i32_e32 v205, 31, v204
	v_ashrrev_i32_e32 v207, 31, v206
	v_writelane_b32 v254, s4, 16
	v_lshl_add_u32 v213, v8, 6, 0
	v_lshl_add_u64 v[210:211], v[96:97], 2, s[52:53]
	v_writelane_b32 v254, s5, 17
	v_cmp_eq_u32_e64 s[4:5], 24, v96
	s_mov_b32 s60, 0
	v_mov_b32_e32 v212, v96
	v_writelane_b32 v254, s4, 18
	v_mov_b32_e32 v99, v96
	v_or_b32_e32 v239, 1, v2
	v_writelane_b32 v254, s5, 19
	v_cmp_eq_u32_e64 s[4:5], 23, v96
	v_lshlrev_b32_e32 v220, 1, v0
	v_add_u32_e32 v240, v6, v7
	v_writelane_b32 v254, s4, 20
	v_add_u32_e32 v241, v6, v1
	v_add_u32_e32 v242, v9, v10
	v_writelane_b32 v254, s5, 21
	v_cmp_eq_u32_e64 s[4:5], 22, v96
	s_nop 1
	v_writelane_b32 v254, s4, 22
	s_nop 1
	v_writelane_b32 v254, s5, 23
	v_cmp_eq_u32_e64 s[4:5], 21, v96
	s_nop 1
	v_writelane_b32 v254, s4, 24
	s_nop 1
	v_writelane_b32 v254, s5, 25
	v_cmp_eq_u32_e64 s[4:5], 20, v96
	s_nop 1
	v_writelane_b32 v254, s4, 26
	s_nop 1
	v_writelane_b32 v254, s5, 27
	v_cmp_eq_u32_e64 s[4:5], 19, v96
	s_nop 1
	v_writelane_b32 v254, s4, 28
	s_nop 1
	v_writelane_b32 v254, s5, 29
	v_cmp_eq_u32_e64 s[4:5], 18, v96
	s_nop 1
	v_writelane_b32 v254, s4, 30
	s_nop 1
	v_writelane_b32 v254, s5, 31
	v_cmp_eq_u32_e64 s[4:5], 17, v96
	s_nop 1
	v_writelane_b32 v254, s4, 32
	s_nop 1
	v_writelane_b32 v254, s5, 33
	v_cmp_eq_u32_e64 s[4:5], 16, v96
	s_nop 1
	v_writelane_b32 v254, s4, 34
	s_nop 1
	v_writelane_b32 v254, s5, 35
	v_cmp_eq_u32_e64 s[4:5], 15, v96
	s_nop 1
	v_writelane_b32 v254, s4, 36
	s_nop 1
	v_writelane_b32 v254, s5, 37
	v_cmp_eq_u32_e64 s[4:5], 14, v96
	s_nop 1
	v_writelane_b32 v254, s4, 38
	s_nop 1
	v_writelane_b32 v254, s5, 39
	v_cmp_eq_u32_e64 s[4:5], 13, v96
	s_nop 1
	v_writelane_b32 v254, s4, 40
	s_nop 1
	v_writelane_b32 v254, s5, 41
	v_cmp_eq_u32_e64 s[4:5], 12, v96
	s_nop 1
	v_writelane_b32 v254, s4, 42
	s_nop 1
	v_writelane_b32 v254, s5, 43
	v_cmp_eq_u32_e64 s[4:5], 11, v96
	s_nop 1
	v_writelane_b32 v254, s4, 44
	s_nop 1
	v_writelane_b32 v254, s5, 45
	v_cmp_eq_u32_e64 s[4:5], 10, v96
	s_nop 1
	v_writelane_b32 v254, s4, 46
	s_nop 1
	v_writelane_b32 v254, s5, 47
	v_cmp_eq_u32_e64 s[4:5], 9, v96
	s_nop 1
	v_writelane_b32 v254, s4, 48
	s_nop 1
	v_writelane_b32 v254, s5, 49
	v_cmp_eq_u32_e64 s[4:5], 8, v96
	s_nop 1
	v_writelane_b32 v254, s4, 50
	s_nop 1
	v_writelane_b32 v254, s5, 51
	v_cmp_eq_u32_e64 s[4:5], 2, v96
	s_nop 1
	v_writelane_b32 v254, s4, 52
	s_nop 1
	v_writelane_b32 v254, s5, 53
	v_cmp_eq_u32_e64 s[4:5], 1, v96
	s_nop 1
	v_writelane_b32 v254, s4, 54
	s_nop 1
	v_writelane_b32 v254, s5, 55
	v_cmp_eq_u32_e64 s[4:5], 0, v96
	s_nop 1
	v_writelane_b32 v254, s4, 56
	s_nop 1
	v_writelane_b32 v254, s5, 57
	v_cmp_eq_u32_e64 s[4:5], 31, v96
	s_nop 1
	v_writelane_b32 v254, s4, 58
	s_nop 1
	v_writelane_b32 v254, s5, 59
	v_writelane_b32 v254, s2, 60
	s_nop 1
	v_writelane_b32 v254, s3, 61
	v_writelane_b32 v254, s1, 62
	v_writelane_b32 v254, s6, 63
	s_mov_b32 s1, s75
	v_lshl_add_u64 v[216:217], v[4:5], 1, s[2:3]
	v_writelane_b32 v255, s7, 0
	v_writelane_b32 v255, s0, 1
	v_lshl_add_u64 v[218:219], v[96:97], 3, s[6:7]
	s_nop 0
	v_writelane_b32 v255, s1, 2
	v_writelane_b32 v255, s54, 3
	s_nop 1
	v_writelane_b32 v255, s55, 4
	v_writelane_b32 v255, s56, 5
	s_nop 1
	v_writelane_b32 v255, s57, 6
	v_writelane_b32 v255, s66, 7
	s_nop 1
	v_writelane_b32 v255, s67, 8
	v_writelane_b32 v255, s68, 9
	s_nop 1
	v_writelane_b32 v255, s69, 10
	v_writelane_b32 v255, s70, 11
	s_nop 1
	v_writelane_b32 v255, s71, 12
	s_branch .LBB0_434

; #define LAS __attribute__((address_space(3)))
; DI unsigned xb_add(unsigned* p, unsigned v) { return __hip_atomic_fetch_add(p, v, __ATOMIC_RELAXED, __HIP_MEMORY_SCOPE_AGENT); }
; DI unsigned xb_xcc_id() { return (unsigned)__builtin_amdgcn_s_getreg((3 << 11) | 20) & 0xFu; }
; DI void grid_bar(unsigned* bar, volatile LAS unsigned* st, unsigned G, int tid) {
;     asm volatile("s_waitcnt vmcnt(0)" ::: "memory");
;     __syncthreads();
;     if (tid == 0) {
;         __builtin_amdgcn_s_waitcnt(0);
;         const unsigned x = xb_xcc_id();
;         unsigned nloc = st[0], nx = st[1];
;         if (nloc == 0u) { xb_complete(bar, x, G, nloc, nx); st[0] = nloc; st[1] = nx; }
;         const unsigned old = xb_add(&bar[XB_XSUB(x)], 1u);
;         const unsigned gen = old / nloc;
.LBB0_526:
	s_setprio 0
	s_mov_b64 s[2:3], s[66:67]
	s_mov_b32 s0, s73
	v_mbcnt_lo_u32_b32 v0, -1, 0
	v_mbcnt_hi_u32_b32 v0, -1, v0
	s_waitcnt vmcnt(0)
	s_lshl_b32 s0, s0, 6
	v_sub_u32_e32 v0, 0, v0
	v_cmp_eq_u32_e32 vcc, s0, v0
	s_barrier
	s_and_saveexec_b64 s[0:1], vcc
	v_readlane_b32 s70, v253, 62
	v_readlane_b32 s71, v253, 63
	v_readlane_b32 s68, v253, 61
	s_movk_i32 s71, 0x121
	s_cbranch_execz .LBB0_578
	v_readlane_b32 s5, v253, 42
	s_load_dwordx2 s[2:3], s[2:3], 0xc8
	s_waitcnt vmcnt(0) expcnt(0) lgkmcnt(0)
	v_mov_b32_e32 v0, s5
	s_getreg_b32 s4, hwreg(HW_REG_XCC_ID, 0, 4)
	ds_read_b32 v2, v0
	v_readlane_b32 s5, v253, 43
	s_and_b32 s18, s4, 15
	s_waitcnt lgkmcnt(0)
	v_cmp_ne_u32_e32 vcc, 0, v2
	v_mov_b32_e32 v0, s5
	ds_read_b32 v0, v0
	s_cbranch_vccnz .LBB0_542
	s_add_u32 s4, s2, 0x1000
	s_addc_u32 s5, s3, 0
	s_add_u32 s6, s2, 0x1100
	s_addc_u32 s7, s3, 0
	s_add_u32 s8, s2, 0x1200
	s_addc_u32 s9, s3, 0
	s_add_u32 s10, s2, 0x1300
	s_addc_u32 s11, s3, 0
	s_mov_b32 s19, 1
	s_branch .LBB0_530
